# PEER u-pass rewritten: experts partitioned across XCDs (L2-resident U slice), hid exchanged through global buffer + one extra grid barrier; packed-f32 dots, permlane/DPP reduce
# speedup vs baseline: 1.1334x; 1.0179x over previous
; #define AS1 __attribute__((address_space(1)))
; #define REP(ph) for (int rp_ = 0; rp_ < ((DBL == (ph)) ? 2 : 1); ++rp_)
; DI void peer_u_wave(const Params& p, int row, float* wl  ) {
;     ...
;   const float r2 = rsqrtf(((const float AS1*)p.ssq2)[row] * (1.f / 1024.f) + EPS);
;   const unsigned char AS1* EU8 = (const unsigned char AS1*)p.E8;
;   const float AS1* rsp = (const float AS1*)p.rs;
; #pragma unroll 1
;   for (int bt = 0; bt < 2; ++bt) {
;     const int eidv = ((const int AS1*)p.eid)[(size_t)row * 128 + bt * 64 + lane];
;     const float gv = ((const float AS1*)p.gate)[(size_t)row * 128 + bt * 64 + lane];
;     const float rsu = rsp[eidv], rsv = rsp[16384 + eidv];
;     float part[64];
; #pragma unroll
;     for (int e = 0; e < 64; ++e) {
;       const int id = __builtin_amdgcn_readlane(eidv, e);
;       const u32x4 u = *(const u32x4 AS1*)(EU8 + (size_t)id * 1024 + lane * 16);
; __global__ void __launch_bounds__(256, 2) mega(Params pk) {
;     ...
;   REP(11) {
;     const int gw = blockIdx.x * 4 + w, nw = gridDim.x * 4;
;     float* wlw = (float*)smem + w * (17 * 128);
;     __syncthreads();
;     for (int k = 0; gw + k * nw < MT && k < 17; ++k) peer_u_wave(p, gw + k * nw, wlw + k * 128);
.LBB0_1348:
	s_or_b64 exec, exec, s[34:35]
	v_mul_u32_u24_e32 v40, 0x2200, v174
	s_waitcnt lgkmcnt(0)
	s_barrier
	s_barrier
	v_mov_b32_e32 v222, 0x10180
	ds_read_b64 v[222:223], v222
	s_mov_b32 s94, 0x4000000
	s_mov_b32 s95, 0
	s_waitcnt lgkmcnt(0)
	v_readfirstlane_b32 s98, v222
	v_readfirstlane_b32 s99, v223
	s_nop 3
	s_add_u32 s98, s98, 0x4000000
	s_addc_u32 s99, s99, 0
	s_and_saveexec_b64 s[14:15], s[8:9]
	s_cbranch_execz .LBB0_1357
	s_mov_b64 exec, -1
	v_mov_b32_e32 v252, v163
	v_mov_b32_e32 v253, v174
	v_mbcnt_lo_u32_b32 v0, -1, 0
	v_mbcnt_hi_u32_b32 v0, -1, v0
	v_lshlrev_b32_e32 v1, 4, v0
	v_lshlrev_b32_e32 v2, 5, v0
	v_lshlrev_b32_e32 v3, 2, v0
	v_mov_b32_e32 v25, 0
	v_mov_b32_e32 v42, 0xbdd2d3e8
	v_lshlrev_b32_e32 v43, 10, v174
	v_add_u32_e32 v43, 0x1000, v43
	v_add_u32_e32 v67, v43, v3
	ds_write_b32 v67, v25
	ds_write_b32 v67, v25 offset:256
	ds_write_b32 v67, v25 offset:512
	v_mov_b32_e32 v10, 0x10170
	ds_read_b64 v[92:93], v10
	v_mov_b32_e32 v10, 0x10140
	ds_read_b64 v[94:95], v10
	v_mov_b32_e32 v10, 0x101b0
	ds_read_b128 v[96:99], v10
	v_mov_b32_e32 v10, 0x10120
	ds_read_b128 v[100:103], v10
	v_mov_b32_e32 v10, 0x101e8
	ds_read_b64 v[104:105], v10
	v_mov_b32_e32 v10, 0x10200
	ds_read_b64 v[106:107], v10
	s_waitcnt lgkmcnt(0)
	v_readfirstlane_b32 s16, v92
	v_readfirstlane_b32 s17, v93
	v_readfirstlane_b32 s18, v94
	v_readfirstlane_b32 s19, v95
	v_readfirstlane_b32 s20, v96
	v_readfirstlane_b32 s21, v97
	v_readfirstlane_b32 s22, v98
	v_readfirstlane_b32 s23, v99
	v_readfirstlane_b32 s24, v100
	v_readfirstlane_b32 s25, v101
	v_readfirstlane_b32 s26, v102
	v_readfirstlane_b32 s27, v103
	v_readfirstlane_b32 s40, v104
	v_readfirstlane_b32 s41, v105
	v_readfirstlane_b32 s72, v106
	v_readfirstlane_b32 s31, v107
	s_getreg_b32 s64, hwreg(HW_REG_XCC_ID, 0, 4)
	s_add_u32 s28, s26, 0x10000
	s_addc_u32 s29, s27, 0
	v_and_b32_e32 v10, 15, v0
	v_lshlrev_b32_e32 v10, 8, v10
	global_load_dword v11, v10, s[40:41] offset:1024 sc1
	v_readlane_b32 s66, v255, 0
	v_readlane_b32 s67, v255, 1
	s_mov_b64 s[68:69], exec
	s_and_b64 exec, exec, s[66:67]
	s_cbranch_execz .Lu3_noli
	s_lshl_b32 s65, s64, 2
	s_add_u32 s70, s40, s65
	s_addc_u32 s71, s41, 0
	v_mov_b32_e32 v92, s70
	v_mov_b32_e32 v93, s71
	v_mov_b32_e32 v94, 1
	flat_atomic_add v95, v[92:93], v94 sc0
	s_waitcnt vmcnt(0) lgkmcnt(0)
	ds_write_b32 v25, v95
	s_waitcnt lgkmcnt(0)
.Lu3_noli:
	s_mov_b64 exec, s[68:69]
	s_waitcnt vmcnt(0)
	s_barrier
	ds_read_b32 v10, v25
	v_cmp_ne_u32_e64 s[66:67], 0, v11
	s_and_b32 s66, s66, 0xffff
	s_lshl_b32 s65, 1, s64
	s_sub_u32 s65, s65, 1
	s_and_b32 s65, s65, s66
	s_bcnt1_i32_b32 s30, s65
	s_mov_b32 s38, 0xff00ff00
	s_mov_b32 s39, 0xff00ff00
	s_mov_b32 s87, 0x800000
	s_waitcnt lgkmcnt(0)
	v_readfirstlane_b32 s65, v10
	v_readfirstlane_b32 s66, v174
	s_lshl_b32 s34, s65, 2
	s_add_u32 s34, s34, s66
	s_lshl_b32 s35, s72, 2
	s_mov_b32 s89, 0
	s_mov_b32 s92, 0
	s_mov_b32 s96, 0
	s_mov_b32 s88, 1
	s_cmp_ge_u32 s34, 32896
	s_cbranch_scc1 .Lu3_done
	s_lshl_b32 s63, s34, 11
	s_add_u32 s40, s16, s63
	s_addc_u32 s41, s17, 0
	global_load_dwordx4 v[12:15], v2, s[40:41]
	global_load_dwordx4 v[16:19], v2, s[40:41] offset:16
	s_lshl_b32 s63, s34, 9
	s_add_u32 s70, s20, s63
	s_addc_u32 s71, s21, 0
	global_load_dword v20, v3, s[70:71]
	global_load_dword v21, v3, s[70:71] offset:256
	s_add_u32 s40, s22, s63
	s_addc_u32 s41, s23, 0
	global_load_dword v22, v3, s[40:41]
	global_load_dword v23, v3, s[40:41] offset:256
	s_lshl_b32 s63, s34, 2
	s_add_u32 s70, s18, s63
	s_addc_u32 s71, s19, 0
	global_load_dword v24, v25, s[70:71]
	s_waitcnt vmcnt(0)
.Lu3_top:
	s_cmp_eq_u32 s88, 0
	s_cbranch_scc1 .Lu3_tailchk
	v_mul_u32_u24_e32 v10, s31, v20
	v_mul_u32_u24_e32 v11, s31, v21
	v_lshrrev_b32_e32 v10, 14, v10
	v_lshrrev_b32_e32 v11, 14, v11
	v_cmp_eq_u32_e64 s[0:1], s30, v10
	v_cmp_eq_u32_e64 s[2:3], s30, v11
	v_lshlrev_b32_e32 v134, 2, v20
	v_lshlrev_b32_e32 v135, 2, v21
	s_bcnt1_i32_b64 s97, s[0:1]
	s_bcnt1_i32_b64 s5, s[2:3]
	s_add_u32 s5, s5, s97
	v_mbcnt_lo_u32_b32 v7, s0, 0
	v_mbcnt_hi_u32_b32 v7, s1, v7
	v_mbcnt_lo_u32_b32 v8, s2, 0
	v_mbcnt_hi_u32_b32 v8, s3, v8
	v_add_u32_e32 v8, s97, v8
	v_lshl_add_u32 v10, v7, 2, v43
	v_lshl_add_u32 v11, v8, 2, v43
	s_min_u32 s58, s5, 24
	s_mov_b64 exec, s[0:1]
	ds_write_b32 v10, v20
	global_load_dword v124, v134, s[26:27]
	global_load_dword v126, v134, s[28:29]
	s_mov_b64 exec, s[2:3]
	ds_write_b32 v11, v21
	global_load_dword v125, v135, s[26:27]
	global_load_dword v127, v135, s[28:29]
	s_mov_b64 exec, -1
	ds_read_b32 v254, v67
	s_waitcnt lgkmcnt(0)
; #define AS1 __attribute__((address_space(1)))
; DI void peer_u_wave(const Params& p, int row, float* wl  ) {
;     ...
; #pragma unroll
;     for (int e = 0; e < 64; ++e) {
;       const int id = __builtin_amdgcn_readlane(eidv, e);
;       const u32x4 u = *(const u32x4 AS1*)(EU8 + (size_t)id * 1024 + lane * 16);
;       part[e] = dot16_fp8(u, xf, 0.f);
;     }
; #pragma unroll
;     for (int off = 32; off > 0; off >>= 1) {
;       const bool up = (lane & off) != 0;
; #pragma unroll
;       for (int i = 0; i < off; ++i) {
;         const float a = part[i], bq = part[i + off];
;         const float send = up ? a : bq, keep = up ? bq : a;
;         part[i] = keep + __shfl_xor(send, off);
;       }
;     }
.Lu3_gather:
	s_cmp_le_u32 s58, 0
	s_cbranch_scc1 .Lu3_gdone
	v_readlane_b32 s64, v254, 0
	v_readlane_b32 s65, v254, 1
	v_readlane_b32 s100, v254, 2
	v_readlane_b32 s101, v254, 3
	v_lshl_add_u32 v4, s64, 10, v1
	v_lshl_add_u32 v5, s65, 10, v1
	v_lshl_add_u32 v6, s100, 10, v1
	v_lshl_add_u32 v9, s101, 10, v1
	global_load_dwordx4 v[156:159], v4, s[24:25]
	global_load_dwordx4 v[160:163], v5, s[24:25]
	global_load_dwordx4 v[164:167], v6, s[24:25]
	global_load_dwordx4 v[168:171], v9, s[24:25]
	s_cmp_le_u32 s58, 4
	s_cbranch_scc1 .Lu3_gdone
	v_readlane_b32 s64, v254, 4
	v_readlane_b32 s65, v254, 5
	v_readlane_b32 s100, v254, 6
	v_readlane_b32 s101, v254, 7
	v_lshl_add_u32 v4, s64, 10, v1
	v_lshl_add_u32 v5, s65, 10, v1
	v_lshl_add_u32 v6, s100, 10, v1
	v_lshl_add_u32 v9, s101, 10, v1
	global_load_dwordx4 v[172:175], v4, s[24:25]
	global_load_dwordx4 v[176:179], v5, s[24:25]
	global_load_dwordx4 v[180:183], v6, s[24:25]
	global_load_dwordx4 v[184:187], v9, s[24:25]
	s_cmp_le_u32 s58, 8
	s_cbranch_scc1 .Lu3_gdone
	v_readlane_b32 s64, v254, 8
	v_readlane_b32 s65, v254, 9
	v_readlane_b32 s100, v254, 10
	v_readlane_b32 s101, v254, 11
	v_lshl_add_u32 v4, s64, 10, v1
	v_lshl_add_u32 v5, s65, 10, v1
	v_lshl_add_u32 v6, s100, 10, v1
	v_lshl_add_u32 v9, s101, 10, v1
	global_load_dwordx4 v[188:191], v4, s[24:25]
	global_load_dwordx4 v[192:195], v5, s[24:25]
	global_load_dwordx4 v[196:199], v6, s[24:25]
	global_load_dwordx4 v[200:203], v9, s[24:25]
	s_cmp_le_u32 s58, 12
	s_cbranch_scc1 .Lu3_gdone
	v_readlane_b32 s64, v254, 12
	v_readlane_b32 s65, v254, 13
	v_readlane_b32 s100, v254, 14
	v_readlane_b32 s101, v254, 15
	v_lshl_add_u32 v4, s64, 10, v1
	v_lshl_add_u32 v5, s65, 10, v1
	v_lshl_add_u32 v6, s100, 10, v1
	v_lshl_add_u32 v9, s101, 10, v1
	global_load_dwordx4 v[204:207], v4, s[24:25]
	global_load_dwordx4 v[208:211], v5, s[24:25]
	global_load_dwordx4 v[212:215], v6, s[24:25]
	global_load_dwordx4 v[216:219], v9, s[24:25]
	s_cmp_le_u32 s58, 16
	s_cbranch_scc1 .Lu3_gdone
	v_readlane_b32 s64, v254, 16
	v_readlane_b32 s65, v254, 17
	v_readlane_b32 s100, v254, 18
	v_readlane_b32 s101, v254, 19
	v_lshl_add_u32 v4, s64, 10, v1
	v_lshl_add_u32 v5, s65, 10, v1
	v_lshl_add_u32 v6, s100, 10, v1
	v_lshl_add_u32 v9, s101, 10, v1
	global_load_dwordx4 v[220:223], v4, s[24:25]
	global_load_dwordx4 v[224:227], v5, s[24:25]
	global_load_dwordx4 v[228:231], v6, s[24:25]
	global_load_dwordx4 v[232:235], v9, s[24:25]
	s_cmp_le_u32 s58, 20
	s_cbranch_scc1 .Lu3_gdone
	v_readlane_b32 s64, v254, 20
	v_readlane_b32 s65, v254, 21
	v_readlane_b32 s100, v254, 22
	v_readlane_b32 s101, v254, 23
	v_lshl_add_u32 v4, s64, 10, v1
	v_lshl_add_u32 v5, s65, 10, v1
	v_lshl_add_u32 v6, s100, 10, v1
	v_lshl_add_u32 v9, s101, 10, v1
	global_load_dwordx4 v[236:239], v4, s[24:25]
	global_load_dwordx4 v[240:243], v5, s[24:25]
	global_load_dwordx4 v[244:247], v6, s[24:25]
	global_load_dwordx4 v[248:251], v9, s[24:25]
.Lu3_gdone:
	s_cmp_lg_u32 s96, 0
	s_cbranch_scc1 .Lu3_ovf_g2
.Lu3_tailchk:
	s_cmp_eq_u32 s89, 0
	s_cbranch_scc1 .Lu3_notail
.Lu3_tail:
	s_cmp_eq_u32 s91, 0
	s_cbranch_scc1 .Lu3_taildel
	s_cmp_gt_u32 s91, 16
	s_cbranch_scc1 .Lu3_red3
	s_cmp_gt_u32 s91, 8
	s_cbranch_scc1 .Lu3_red2
	s_nop 1
	v_permlane32_swap_b32 v68, v69
	v_permlane32_swap_b32 v70, v71
	v_permlane32_swap_b32 v72, v73
	v_permlane32_swap_b32 v74, v75
	v_add_f32_e32 v68, v68, v69
	v_add_f32_e32 v70, v70, v71
	v_add_f32_e32 v72, v72, v73
	v_add_f32_e32 v74, v74, v75
	s_nop 1
	v_permlane16_swap_b32 v68, v70
	v_permlane16_swap_b32 v72, v74
	v_add_f32_e32 v68, v68, v70
	v_add_f32_e32 v72, v72, v74
	v_cndmask_b32_e64 v69, v72, v68, s[38:39]
	v_cndmask_b32_e64 v70, v68, v72, s[38:39]
	s_nop 1
	v_add_f32_dpp v144, v69, v70 row_ror:8 row_mask:0xf bank_mask:0xf
	s_nop 1
	v_add_f32_dpp v147, v144, v144 quad_perm:[1,0,3,2] row_mask:0xf bank_mask:0xf
	s_nop 1
	v_add_f32_dpp v144, v147, v147 quad_perm:[2,3,0,1] row_mask:0xf bank_mask:0xf
	s_nop 1
	v_add_f32_dpp v147, v144, v144 row_half_mirror row_mask:0xf bank_mask:0xf
	s_nop 1
	ds_bpermute_b32 v92, v130, v147
	ds_bpermute_b32 v93, v131, v147
	v_cmp_eq_u32_e64 s[70:71], s59, v132
	v_cmp_eq_u32_e64 s[72:73], s59, v133
	s_nop 1
	s_waitcnt lgkmcnt(0)
	v_cndmask_b32_e64 v65, v65, v92, s[70:71]
	v_cndmask_b32_e64 v66, v66, v93, s[72:73]
	s_branch .Lu3_taildel
.Lu3_red2:
	s_nop 1
	v_permlane32_swap_b32 v68, v69
	v_permlane32_swap_b32 v70, v71
	v_permlane32_swap_b32 v72, v73
	v_permlane32_swap_b32 v74, v75
	v_permlane32_swap_b32 v76, v77
	v_permlane32_swap_b32 v78, v79
	v_permlane32_swap_b32 v80, v81
	v_permlane32_swap_b32 v82, v83
	v_add_f32_e32 v68, v68, v69
	v_add_f32_e32 v70, v70, v71
	v_add_f32_e32 v72, v72, v73
	v_add_f32_e32 v74, v74, v75
	v_add_f32_e32 v76, v76, v77
	v_add_f32_e32 v78, v78, v79
	v_add_f32_e32 v80, v80, v81
	v_add_f32_e32 v82, v82, v83
	s_nop 1
	v_permlane16_swap_b32 v68, v70
	v_permlane16_swap_b32 v72, v74
	v_permlane16_swap_b32 v76, v78
	v_permlane16_swap_b32 v80, v82
	v_add_f32_e32 v68, v68, v70
	v_add_f32_e32 v72, v72, v74
	v_add_f32_e32 v76, v76, v78
	v_add_f32_e32 v80, v80, v82
	v_cndmask_b32_e64 v69, v72, v68, s[38:39]
	v_cndmask_b32_e64 v70, v68, v72, s[38:39]
	v_cndmask_b32_e64 v77, v80, v76, s[38:39]
	v_cndmask_b32_e64 v78, v76, v80, s[38:39]
	s_nop 1
	v_add_f32_dpp v144, v69, v70 row_ror:8 row_mask:0xf bank_mask:0xf
	v_add_f32_dpp v145, v77, v78 row_ror:8 row_mask:0xf bank_mask:0xf
	s_nop 1
	v_add_f32_dpp v147, v144, v144 quad_perm:[1,0,3,2] row_mask:0xf bank_mask:0xf
	v_add_f32_dpp v148, v145, v145 quad_perm:[1,0,3,2] row_mask:0xf bank_mask:0xf
	s_nop 1
	v_add_f32_dpp v144, v147, v147 quad_perm:[2,3,0,1] row_mask:0xf bank_mask:0xf
	v_add_f32_dpp v145, v148, v148 quad_perm:[2,3,0,1] row_mask:0xf bank_mask:0xf
	s_nop 1
	v_add_f32_dpp v147, v144, v144 row_half_mirror row_mask:0xf bank_mask:0xf
	v_add_f32_dpp v148, v145, v145 row_half_mirror row_mask:0xf bank_mask:0xf
	s_nop 1
	ds_bpermute_b32 v92, v130, v147
	ds_bpermute_b32 v93, v131, v147
	ds_bpermute_b32 v94, v130, v148
	ds_bpermute_b32 v95, v131, v148
	v_cmp_eq_u32_e64 s[70:71], s59, v132
	v_cmp_eq_u32_e64 s[72:73], s59, v133
	s_add_u32 s100, s59, 1
	v_cmp_eq_u32_e64 s[74:75], s100, v132
	v_cmp_eq_u32_e64 s[76:77], s100, v133
	s_nop 1
	s_waitcnt lgkmcnt(0)
	v_cndmask_b32_e64 v65, v65, v92, s[70:71]
	v_cndmask_b32_e64 v66, v66, v93, s[72:73]
	v_cndmask_b32_e64 v65, v65, v94, s[74:75]
	v_cndmask_b32_e64 v66, v66, v95, s[76:77]
	s_branch .Lu3_taildel
; #define AS1 __attribute__((address_space(1)))
; DI float bflo(unsigned d) { return __uint_as_float(d << 16); }
; DI float bfhi(unsigned d) { return __uint_as_float(d & 0xffff0000u); }
; DI float geluf(float x) { return 0.5f * x * (1.f + tanhf(0.7978845608028654f * (x + 0.044715f * x * x * x))); }
; DI void peer_u_wave(const Params& p, int row, float* wl  ) {
;   const int lane = __builtin_amdgcn_mbcnt_hi(-1, __builtin_amdgcn_mbcnt_lo(-1, 0));
;   float xf[16];
;   {
;     const u32x4 x0 = *(const u32x4 AS1*)((const u16 AS1*)p.h2 + (size_t)row * 1024 + lane * 16);
;     const u32x4 x1 = *(const u32x4 AS1*)((const u16 AS1*)p.h2 + (size_t)row * 1024 + lane * 16 + 8);
;     xf[0] = bflo(x0[0]); xf[1] = bfhi(x0[0]); xf[2] = bflo(x0[1]); xf[3] = bfhi(x0[1]);
;     xf[4] = bflo(x0[2]); xf[5] = bfhi(x0[2]); xf[6] = bflo(x0[3]); xf[7] = bfhi(x0[3]);
;     xf[8] = bflo(x1[0]); xf[9] = bfhi(x1[0]); xf[10] = bflo(x1[1]); xf[11] = bfhi(x1[1]);
;     xf[12] = bflo(x1[2]); xf[13] = bfhi(x1[2]); xf[14] = bflo(x1[3]); xf[15] = bfhi(x1[3]);
;   }
;   const float r2 = rsqrtf(((const float AS1*)p.ssq2)[row] * (1.f / 1024.f) + EPS);
;   const unsigned char AS1* EU8 = (const unsigned char AS1*)p.E8;
;   const float AS1* rsp = (const float AS1*)p.rs;
; #pragma unroll 1
;   for (int bt = 0; bt < 2; ++bt) {
;     const int eidv = ((const int AS1*)p.eid)[(size_t)row * 128 + bt * 64 + lane];
;     const float gv = ((const float AS1*)p.gate)[(size_t)row * 128 + bt * 64 + lane];
;     const float rsu = rsp[eidv], rsv = rsp[16384 + eidv];
;     ...
; #pragma unroll
;     for (int off = 32; off > 0; off >>= 1) {
;       const bool up = (lane & off) != 0;
; #pragma unroll
;       for (int i = 0; i < off; ++i) {
;         const float a = part[i], bq = part[i + off];
;         const float send = up ? a : bq, keep = up ? bq : a;
;         part[i] = keep + __shfl_xor(send, off);
;       }
;     }
;     wl[bt * 64 + lane] = gv * geluf(part[0] * r2 * rsu) * rsv;
.Lu3_red3:
	s_nop 1
	v_permlane32_swap_b32 v68, v69
	v_permlane32_swap_b32 v70, v71
	v_permlane32_swap_b32 v72, v73
	v_permlane32_swap_b32 v74, v75
	v_permlane32_swap_b32 v76, v77
	v_permlane32_swap_b32 v78, v79
	v_permlane32_swap_b32 v80, v81
	v_permlane32_swap_b32 v82, v83
	v_permlane32_swap_b32 v84, v85
	v_permlane32_swap_b32 v86, v87
	v_permlane32_swap_b32 v88, v89
	v_permlane32_swap_b32 v90, v91
	v_add_f32_e32 v68, v68, v69
	v_add_f32_e32 v70, v70, v71
	v_add_f32_e32 v72, v72, v73
	v_add_f32_e32 v74, v74, v75
	v_add_f32_e32 v76, v76, v77
	v_add_f32_e32 v78, v78, v79
	v_add_f32_e32 v80, v80, v81
	v_add_f32_e32 v82, v82, v83
	v_add_f32_e32 v84, v84, v85
	v_add_f32_e32 v86, v86, v87
	v_add_f32_e32 v88, v88, v89
	v_add_f32_e32 v90, v90, v91
	s_nop 1
	v_permlane16_swap_b32 v68, v70
	v_permlane16_swap_b32 v72, v74
	v_permlane16_swap_b32 v76, v78
	v_permlane16_swap_b32 v80, v82
	v_permlane16_swap_b32 v84, v86
	v_permlane16_swap_b32 v88, v90
	v_add_f32_e32 v68, v68, v70
	v_add_f32_e32 v72, v72, v74
	v_add_f32_e32 v76, v76, v78
	v_add_f32_e32 v80, v80, v82
	v_add_f32_e32 v84, v84, v86
	v_add_f32_e32 v88, v88, v90
	v_cndmask_b32_e64 v69, v72, v68, s[38:39]
	v_cndmask_b32_e64 v70, v68, v72, s[38:39]
	v_cndmask_b32_e64 v77, v80, v76, s[38:39]
	v_cndmask_b32_e64 v78, v76, v80, s[38:39]
	v_cndmask_b32_e64 v85, v88, v84, s[38:39]
	v_cndmask_b32_e64 v86, v84, v88, s[38:39]
	s_nop 1
	v_add_f32_dpp v144, v69, v70 row_ror:8 row_mask:0xf bank_mask:0xf
	v_add_f32_dpp v145, v77, v78 row_ror:8 row_mask:0xf bank_mask:0xf
	v_add_f32_dpp v146, v85, v86 row_ror:8 row_mask:0xf bank_mask:0xf
	s_nop 1
	v_add_f32_dpp v147, v144, v144 quad_perm:[1,0,3,2] row_mask:0xf bank_mask:0xf
	v_add_f32_dpp v148, v145, v145 quad_perm:[1,0,3,2] row_mask:0xf bank_mask:0xf
	v_add_f32_dpp v149, v146, v146 quad_perm:[1,0,3,2] row_mask:0xf bank_mask:0xf
	s_nop 1
	v_add_f32_dpp v144, v147, v147 quad_perm:[2,3,0,1] row_mask:0xf bank_mask:0xf
	v_add_f32_dpp v145, v148, v148 quad_perm:[2,3,0,1] row_mask:0xf bank_mask:0xf
	v_add_f32_dpp v146, v149, v149 quad_perm:[2,3,0,1] row_mask:0xf bank_mask:0xf
	s_nop 1
	v_add_f32_dpp v147, v144, v144 row_half_mirror row_mask:0xf bank_mask:0xf
	v_add_f32_dpp v148, v145, v145 row_half_mirror row_mask:0xf bank_mask:0xf
	v_add_f32_dpp v149, v146, v146 row_half_mirror row_mask:0xf bank_mask:0xf
	s_nop 1
	ds_bpermute_b32 v92, v130, v147
	ds_bpermute_b32 v93, v131, v147
	ds_bpermute_b32 v94, v130, v148
	ds_bpermute_b32 v95, v131, v148
	ds_bpermute_b32 v96, v130, v149
	ds_bpermute_b32 v97, v131, v149
	v_cmp_eq_u32_e64 s[70:71], s59, v132
	v_cmp_eq_u32_e64 s[72:73], s59, v133
	s_add_u32 s100, s59, 1
	v_cmp_eq_u32_e64 s[74:75], s100, v132
	v_cmp_eq_u32_e64 s[76:77], s100, v133
	s_add_u32 s100, s59, 2
	v_cmp_eq_u32_e64 s[62:63], s100, v132
	v_cmp_eq_u32_e64 s[64:65], s100, v133
	s_nop 1
	s_waitcnt lgkmcnt(0)
	v_cndmask_b32_e64 v65, v65, v92, s[70:71]
	v_cndmask_b32_e64 v66, v66, v93, s[72:73]
	v_cndmask_b32_e64 v65, v65, v94, s[74:75]
	v_cndmask_b32_e64 v66, v66, v95, s[76:77]
	v_cndmask_b32_e64 v65, v65, v96, s[62:63]
	v_cndmask_b32_e64 v66, v66, v97, s[64:65]
.Lu3_taildel:
	s_cmp_lg_u32 s92, 0
	s_cbranch_scc1 .Lu3_ovf_cont
	s_lshl_b32 s63, s93, 9
	s_add_u32 s40, s98, s63
	s_addc_u32 s41, s99, 0
	v_mul_f32_e32 v150, v60, v65
	v_mul_f32_e32 v150, v61, v150
	v_mul_f32_e32 v151, v150, v150
	v_fmaak_f32 v152, v151, v42, 0xc0135761
	v_mul_f32_e32 v153, v150, v152
	v_exp_f32_e32 v154, v153
	s_nop 0
	v_add_f32_e32 v154, 1.0, v154
	v_rcp_f32_e32 v154, v154
	s_nop 0
	v_mul_f32_e32 v155, v150, v154
	v_mul_f32_e32 v155, v26, v155
	v_mul_f32_e32 v155, v63, v155
	s_mov_b64 exec, s[66:67]
	s_cbranch_execz .Lu3_nost_0
	global_store_dword v3, v155, s[40:41]
.Lu3_nost_0:
	s_mov_b64 exec, -1
	v_mul_f32_e32 v150, v60, v66
	v_mul_f32_e32 v150, v62, v150
	v_mul_f32_e32 v151, v150, v150
	v_fmaak_f32 v152, v151, v42, 0xc0135761
	v_mul_f32_e32 v153, v150, v152
	v_exp_f32_e32 v154, v153
	s_nop 0
	v_add_f32_e32 v154, 1.0, v154
	v_rcp_f32_e32 v154, v154
	s_nop 0
	v_mul_f32_e32 v155, v150, v154
	v_mul_f32_e32 v155, v27, v155
	v_mul_f32_e32 v155, v64, v155
	s_mov_b64 exec, s[68:69]
	s_cbranch_execz .Lu3_nost_1
	global_store_dword v3, v155, s[40:41] offset:256
.Lu3_nost_1:
	s_mov_b64 exec, -1
.Lu3_notail:
	s_cmp_eq_u32 s88, 0
	s_cbranch_scc1 .Lu3_done
	s_add_u32 s36, s34, s35
	s_cmp_lt_u32 s36, 32896
	s_cselect_b32 s37, 1, 0
	s_min_u32 s7, s36, 32895
	s_lshl_b32 s63, s7, 11
	s_add_u32 s40, s16, s63
	s_addc_u32 s41, s17, 0
	global_load_dwordx4 v[28:31], v2, s[40:41]
	global_load_dwordx4 v[32:35], v2, s[40:41] offset:16
	s_lshl_b32 s63, s7, 9
	s_add_u32 s70, s20, s63
	s_addc_u32 s71, s21, 0
	global_load_dword v36, v3, s[70:71]
	global_load_dword v37, v3, s[70:71] offset:256
	s_add_u32 s40, s22, s63
	s_addc_u32 s41, s23, 0
	global_load_dword v38, v3, s[40:41]
	global_load_dword v39, v3, s[40:41] offset:256
	s_lshl_b32 s63, s7, 2
	s_add_u32 s70, s18, s63
	s_addc_u32 s71, s19, 0
	global_load_dword v41, v25, s[70:71]
	s_mov_b64 s[66:67], s[0:1]
	s_mov_b64 s[68:69], s[2:3]
	v_lshrrev_b32_e32 v132, 3, v7
	v_and_b32_e32 v130, 7, v7
	v_bfrev_b32_e32 v130, v130
	v_lshrrev_b32_e32 v130, 24, v130
	v_lshrrev_b32_e32 v133, 3, v8
	v_and_b32_e32 v131, 7, v8
	v_bfrev_b32_e32 v131, v131
	v_lshrrev_b32_e32 v131, 24, v131
	s_mov_b32 s93, s34
	s_mov_b32 s91, s58
	s_sub_i32 s4, s5, 24
	s_mov_b32 s59, 0
	v_mov_b32_e32 v26, v22
	v_mov_b32_e32 v27, v23
	s_waitcnt vmcnt(7)
	v_lshlrev_b32_e32 v44, 16, v12
	v_and_b32_e32 v45, 0xffff0000, v12
	v_lshlrev_b32_e32 v46, 16, v13
	v_and_b32_e32 v47, 0xffff0000, v13
	v_lshlrev_b32_e32 v48, 16, v14
	v_and_b32_e32 v49, 0xffff0000, v14
	v_lshlrev_b32_e32 v50, 16, v15
	v_and_b32_e32 v51, 0xffff0000, v15
	v_lshlrev_b32_e32 v52, 16, v16
	v_and_b32_e32 v53, 0xffff0000, v16
	v_lshlrev_b32_e32 v54, 16, v17
	v_and_b32_e32 v55, 0xffff0000, v17
	v_lshlrev_b32_e32 v56, 16, v18
	v_and_b32_e32 v57, 0xffff0000, v18
	v_lshlrev_b32_e32 v58, 16, v19
	v_and_b32_e32 v59, 0xffff0000, v19
	v_mov_b32_e32 v61, v124
	v_mov_b32_e32 v62, v125
	v_mov_b32_e32 v63, v126
	v_mov_b32_e32 v64, v127
	v_mov_b32_e32 v10, 0x358637bd
	v_fmamk_f32 v10, v24, 0x3a800000, v10
	v_mul_f32_e32 v11, 0x4b800000, v10
	v_cmp_gt_f32_e32 vcc, s87, v10
	s_nop 1
	v_cndmask_b32_e32 v10, v10, v11, vcc
	v_rsq_f32_e32 v10, v10
	s_nop 0
	v_mul_f32_e32 v11, 0x45800000, v10
	v_cndmask_b32_e32 v60, v10, v11, vcc
; #define AS1 __attribute__((address_space(1)))
; DI float dot16_fp8(u32x4 u, const float* x, float c) {
;   const unsigned d[4] = {u[0], u[1], u[2], u[3]};
; #pragma unroll
;   for (int i = 0; i < 4; ++i) {
;     f32x2 a = __builtin_amdgcn_cvt_pk_f32_fp8((int)d[i], false);
;     f32x2 b = __builtin_amdgcn_cvt_pk_f32_fp8((int)d[i], true);
;     c += a[0] * x[4 * i] + a[1] * x[4 * i + 1] + b[0] * x[4 * i + 2] + b[1] * x[4 * i + 3];
;   }
;   return c;
; }
; DI void peer_u_wave(const Params& p, int row, float* wl  ) {
;     ...
; #pragma unroll
;     for (int e = 0; e < 64; ++e) {
;       const int id = __builtin_amdgcn_readlane(eidv, e);
;       const u32x4 u = *(const u32x4 AS1*)(EU8 + (size_t)id * 1024 + lane * 16);
;       part[e] = dot16_fp8(u, xf, 0.f);
;     }
.Lu3_dots:
	s_cmp_le_u32 s91, 0
	s_cbranch_scc1 .Lu3_dotsdone
	v_cvt_pk_f32_fp8_e32 v[92:93], v156
	v_cvt_pk_f32_fp8_e32 v[108:109], v160
	v_cvt_pk_f32_fp8_sdwa v[94:95], v156 src0_sel:WORD_1
	v_cvt_pk_f32_fp8_sdwa v[110:111], v160 src0_sel:WORD_1
	v_cvt_pk_f32_fp8_e32 v[96:97], v157
	v_cvt_pk_f32_fp8_e32 v[112:113], v161
	v_cvt_pk_f32_fp8_sdwa v[98:99], v157 src0_sel:WORD_1
	v_cvt_pk_f32_fp8_sdwa v[114:115], v161 src0_sel:WORD_1
	v_cvt_pk_f32_fp8_e32 v[100:101], v158
	v_cvt_pk_f32_fp8_e32 v[116:117], v162
	v_cvt_pk_f32_fp8_sdwa v[102:103], v158 src0_sel:WORD_1
	v_cvt_pk_f32_fp8_sdwa v[118:119], v162 src0_sel:WORD_1
	v_cvt_pk_f32_fp8_e32 v[104:105], v159
	v_cvt_pk_f32_fp8_e32 v[120:121], v163
	v_cvt_pk_f32_fp8_sdwa v[106:107], v159 src0_sel:WORD_1
	v_cvt_pk_f32_fp8_sdwa v[122:123], v163 src0_sel:WORD_1
	v_pk_mul_f32 v[136:137], v[92:93], v[44:45]
	v_pk_mul_f32 v[140:141], v[108:109], v[44:45]
	v_pk_mul_f32 v[138:139], v[100:101], v[52:53]
	v_pk_mul_f32 v[142:143], v[116:117], v[52:53]
	v_pk_fma_f32 v[136:137], v[94:95], v[46:47], v[136:137]
	v_pk_fma_f32 v[140:141], v[110:111], v[46:47], v[140:141]
	v_pk_fma_f32 v[138:139], v[102:103], v[54:55], v[138:139]
	v_pk_fma_f32 v[142:143], v[118:119], v[54:55], v[142:143]
	v_pk_fma_f32 v[136:137], v[96:97], v[48:49], v[136:137]
	v_pk_fma_f32 v[140:141], v[112:113], v[48:49], v[140:141]
	v_pk_fma_f32 v[138:139], v[104:105], v[56:57], v[138:139]
	v_pk_fma_f32 v[142:143], v[120:121], v[56:57], v[142:143]
	v_pk_fma_f32 v[136:137], v[98:99], v[50:51], v[136:137]
	v_pk_fma_f32 v[140:141], v[114:115], v[50:51], v[140:141]
	v_pk_fma_f32 v[138:139], v[106:107], v[58:59], v[138:139]
	v_pk_fma_f32 v[142:143], v[122:123], v[58:59], v[142:143]
	v_pk_add_f32 v[136:137], v[136:137], v[138:139]
	v_pk_add_f32 v[140:141], v[140:141], v[142:143]
	v_add_f32_e32 v68, v136, v137
	v_add_f32_e32 v69, v140, v141
	s_cmp_le_u32 s91, 2
	s_cbranch_scc1 .Lu3_dotsdone
	v_cvt_pk_f32_fp8_e32 v[92:93], v164
	v_cvt_pk_f32_fp8_e32 v[108:109], v168
	v_cvt_pk_f32_fp8_sdwa v[94:95], v164 src0_sel:WORD_1
	v_cvt_pk_f32_fp8_sdwa v[110:111], v168 src0_sel:WORD_1
	v_cvt_pk_f32_fp8_e32 v[96:97], v165
	v_cvt_pk_f32_fp8_e32 v[112:113], v169
	v_cvt_pk_f32_fp8_sdwa v[98:99], v165 src0_sel:WORD_1
	v_cvt_pk_f32_fp8_sdwa v[114:115], v169 src0_sel:WORD_1
	v_cvt_pk_f32_fp8_e32 v[100:101], v166
	v_cvt_pk_f32_fp8_e32 v[116:117], v170
	v_cvt_pk_f32_fp8_sdwa v[102:103], v166 src0_sel:WORD_1
	v_cvt_pk_f32_fp8_sdwa v[118:119], v170 src0_sel:WORD_1
	v_cvt_pk_f32_fp8_e32 v[104:105], v167
	v_cvt_pk_f32_fp8_e32 v[120:121], v171
	v_cvt_pk_f32_fp8_sdwa v[106:107], v167 src0_sel:WORD_1
	v_cvt_pk_f32_fp8_sdwa v[122:123], v171 src0_sel:WORD_1
	v_pk_mul_f32 v[136:137], v[92:93], v[44:45]
	v_pk_mul_f32 v[140:141], v[108:109], v[44:45]
	v_pk_mul_f32 v[138:139], v[100:101], v[52:53]
	v_pk_mul_f32 v[142:143], v[116:117], v[52:53]
	v_pk_fma_f32 v[136:137], v[94:95], v[46:47], v[136:137]
	v_pk_fma_f32 v[140:141], v[110:111], v[46:47], v[140:141]
	v_pk_fma_f32 v[138:139], v[102:103], v[54:55], v[138:139]
	v_pk_fma_f32 v[142:143], v[118:119], v[54:55], v[142:143]
	v_pk_fma_f32 v[136:137], v[96:97], v[48:49], v[136:137]
	v_pk_fma_f32 v[140:141], v[112:113], v[48:49], v[140:141]
	v_pk_fma_f32 v[138:139], v[104:105], v[56:57], v[138:139]
	v_pk_fma_f32 v[142:143], v[120:121], v[56:57], v[142:143]
	v_pk_fma_f32 v[136:137], v[98:99], v[50:51], v[136:137]
	v_pk_fma_f32 v[140:141], v[114:115], v[50:51], v[140:141]
	v_pk_fma_f32 v[138:139], v[106:107], v[58:59], v[138:139]
	v_pk_fma_f32 v[142:143], v[122:123], v[58:59], v[142:143]
	v_pk_add_f32 v[136:137], v[136:137], v[138:139]
	v_pk_add_f32 v[140:141], v[140:141], v[142:143]
	v_add_f32_e32 v70, v136, v137
	v_add_f32_e32 v71, v140, v141
	s_cmp_le_u32 s91, 4
	s_cbranch_scc1 .Lu3_dotsdone
	v_cvt_pk_f32_fp8_e32 v[92:93], v172
	v_cvt_pk_f32_fp8_e32 v[108:109], v176
	v_cvt_pk_f32_fp8_sdwa v[94:95], v172 src0_sel:WORD_1
	v_cvt_pk_f32_fp8_sdwa v[110:111], v176 src0_sel:WORD_1
	v_cvt_pk_f32_fp8_e32 v[96:97], v173
	v_cvt_pk_f32_fp8_e32 v[112:113], v177
	v_cvt_pk_f32_fp8_sdwa v[98:99], v173 src0_sel:WORD_1
	v_cvt_pk_f32_fp8_sdwa v[114:115], v177 src0_sel:WORD_1
	v_cvt_pk_f32_fp8_e32 v[100:101], v174
	v_cvt_pk_f32_fp8_e32 v[116:117], v178
	v_cvt_pk_f32_fp8_sdwa v[102:103], v174 src0_sel:WORD_1
	v_cvt_pk_f32_fp8_sdwa v[118:119], v178 src0_sel:WORD_1
	v_cvt_pk_f32_fp8_e32 v[104:105], v175
	v_cvt_pk_f32_fp8_e32 v[120:121], v179
	v_cvt_pk_f32_fp8_sdwa v[106:107], v175 src0_sel:WORD_1
	v_cvt_pk_f32_fp8_sdwa v[122:123], v179 src0_sel:WORD_1
	v_pk_mul_f32 v[136:137], v[92:93], v[44:45]
	v_pk_mul_f32 v[140:141], v[108:109], v[44:45]
	v_pk_mul_f32 v[138:139], v[100:101], v[52:53]
	v_pk_mul_f32 v[142:143], v[116:117], v[52:53]
	v_pk_fma_f32 v[136:137], v[94:95], v[46:47], v[136:137]
	v_pk_fma_f32 v[140:141], v[110:111], v[46:47], v[140:141]
	v_pk_fma_f32 v[138:139], v[102:103], v[54:55], v[138:139]
	v_pk_fma_f32 v[142:143], v[118:119], v[54:55], v[142:143]
	v_pk_fma_f32 v[136:137], v[96:97], v[48:49], v[136:137]
	v_pk_fma_f32 v[140:141], v[112:113], v[48:49], v[140:141]
	v_pk_fma_f32 v[138:139], v[104:105], v[56:57], v[138:139]
	v_pk_fma_f32 v[142:143], v[120:121], v[56:57], v[142:143]
	v_pk_fma_f32 v[136:137], v[98:99], v[50:51], v[136:137]
	v_pk_fma_f32 v[140:141], v[114:115], v[50:51], v[140:141]
	v_pk_fma_f32 v[138:139], v[106:107], v[58:59], v[138:139]
	v_pk_fma_f32 v[142:143], v[122:123], v[58:59], v[142:143]
	v_pk_add_f32 v[136:137], v[136:137], v[138:139]
	v_pk_add_f32 v[140:141], v[140:141], v[142:143]
	v_add_f32_e32 v72, v136, v137
	v_add_f32_e32 v73, v140, v141
	s_cmp_le_u32 s91, 6
	s_cbranch_scc1 .Lu3_dotsdone
; #define AS1 __attribute__((address_space(1)))
; DI float dot16_fp8(u32x4 u, const float* x, float c) {
;   const unsigned d[4] = {u[0], u[1], u[2], u[3]};
; #pragma unroll
;   for (int i = 0; i < 4; ++i) {
;     f32x2 a = __builtin_amdgcn_cvt_pk_f32_fp8((int)d[i], false);
;     f32x2 b = __builtin_amdgcn_cvt_pk_f32_fp8((int)d[i], true);
;     c += a[0] * x[4 * i] + a[1] * x[4 * i + 1] + b[0] * x[4 * i + 2] + b[1] * x[4 * i + 3];
;   }
;   return c;
; }
; DI void peer_u_wave(const Params& p, int row, float* wl  ) {
;     ...
; #pragma unroll
;     for (int e = 0; e < 64; ++e) {
;       const int id = __builtin_amdgcn_readlane(eidv, e);
;       const u32x4 u = *(const u32x4 AS1*)(EU8 + (size_t)id * 1024 + lane * 16);
;       part[e] = dot16_fp8(u, xf, 0.f);
;     }
	v_cvt_pk_f32_fp8_e32 v[92:93], v180
	v_cvt_pk_f32_fp8_e32 v[108:109], v184
	v_cvt_pk_f32_fp8_sdwa v[94:95], v180 src0_sel:WORD_1
	v_cvt_pk_f32_fp8_sdwa v[110:111], v184 src0_sel:WORD_1
	v_cvt_pk_f32_fp8_e32 v[96:97], v181
	v_cvt_pk_f32_fp8_e32 v[112:113], v185
	v_cvt_pk_f32_fp8_sdwa v[98:99], v181 src0_sel:WORD_1
	v_cvt_pk_f32_fp8_sdwa v[114:115], v185 src0_sel:WORD_1
	v_cvt_pk_f32_fp8_e32 v[100:101], v182
	v_cvt_pk_f32_fp8_e32 v[116:117], v186
	v_cvt_pk_f32_fp8_sdwa v[102:103], v182 src0_sel:WORD_1
	v_cvt_pk_f32_fp8_sdwa v[118:119], v186 src0_sel:WORD_1
	v_cvt_pk_f32_fp8_e32 v[104:105], v183
	v_cvt_pk_f32_fp8_e32 v[120:121], v187
	v_cvt_pk_f32_fp8_sdwa v[106:107], v183 src0_sel:WORD_1
	v_cvt_pk_f32_fp8_sdwa v[122:123], v187 src0_sel:WORD_1
	v_pk_mul_f32 v[136:137], v[92:93], v[44:45]
	v_pk_mul_f32 v[140:141], v[108:109], v[44:45]
	v_pk_mul_f32 v[138:139], v[100:101], v[52:53]
	v_pk_mul_f32 v[142:143], v[116:117], v[52:53]
	v_pk_fma_f32 v[136:137], v[94:95], v[46:47], v[136:137]
	v_pk_fma_f32 v[140:141], v[110:111], v[46:47], v[140:141]
	v_pk_fma_f32 v[138:139], v[102:103], v[54:55], v[138:139]
	v_pk_fma_f32 v[142:143], v[118:119], v[54:55], v[142:143]
	v_pk_fma_f32 v[136:137], v[96:97], v[48:49], v[136:137]
	v_pk_fma_f32 v[140:141], v[112:113], v[48:49], v[140:141]
	v_pk_fma_f32 v[138:139], v[104:105], v[56:57], v[138:139]
	v_pk_fma_f32 v[142:143], v[120:121], v[56:57], v[142:143]
	v_pk_fma_f32 v[136:137], v[98:99], v[50:51], v[136:137]
	v_pk_fma_f32 v[140:141], v[114:115], v[50:51], v[140:141]
	v_pk_fma_f32 v[138:139], v[106:107], v[58:59], v[138:139]
	v_pk_fma_f32 v[142:143], v[122:123], v[58:59], v[142:143]
	v_pk_add_f32 v[136:137], v[136:137], v[138:139]
	v_pk_add_f32 v[140:141], v[140:141], v[142:143]
	v_add_f32_e32 v74, v136, v137
	v_add_f32_e32 v75, v140, v141
	s_cmp_le_u32 s91, 8
	s_cbranch_scc1 .Lu3_dotsdone
	v_cvt_pk_f32_fp8_e32 v[92:93], v188
	v_cvt_pk_f32_fp8_e32 v[108:109], v192
	v_cvt_pk_f32_fp8_sdwa v[94:95], v188 src0_sel:WORD_1
	v_cvt_pk_f32_fp8_sdwa v[110:111], v192 src0_sel:WORD_1
	v_cvt_pk_f32_fp8_e32 v[96:97], v189
	v_cvt_pk_f32_fp8_e32 v[112:113], v193
	v_cvt_pk_f32_fp8_sdwa v[98:99], v189 src0_sel:WORD_1
	v_cvt_pk_f32_fp8_sdwa v[114:115], v193 src0_sel:WORD_1
	v_cvt_pk_f32_fp8_e32 v[100:101], v190
	v_cvt_pk_f32_fp8_e32 v[116:117], v194
	v_cvt_pk_f32_fp8_sdwa v[102:103], v190 src0_sel:WORD_1
	v_cvt_pk_f32_fp8_sdwa v[118:119], v194 src0_sel:WORD_1
	v_cvt_pk_f32_fp8_e32 v[104:105], v191
	v_cvt_pk_f32_fp8_e32 v[120:121], v195
	v_cvt_pk_f32_fp8_sdwa v[106:107], v191 src0_sel:WORD_1
	v_cvt_pk_f32_fp8_sdwa v[122:123], v195 src0_sel:WORD_1
	v_pk_mul_f32 v[136:137], v[92:93], v[44:45]
	v_pk_mul_f32 v[140:141], v[108:109], v[44:45]
	v_pk_mul_f32 v[138:139], v[100:101], v[52:53]
	v_pk_mul_f32 v[142:143], v[116:117], v[52:53]
	v_pk_fma_f32 v[136:137], v[94:95], v[46:47], v[136:137]
	v_pk_fma_f32 v[140:141], v[110:111], v[46:47], v[140:141]
	v_pk_fma_f32 v[138:139], v[102:103], v[54:55], v[138:139]
	v_pk_fma_f32 v[142:143], v[118:119], v[54:55], v[142:143]
	v_pk_fma_f32 v[136:137], v[96:97], v[48:49], v[136:137]
	v_pk_fma_f32 v[140:141], v[112:113], v[48:49], v[140:141]
	v_pk_fma_f32 v[138:139], v[104:105], v[56:57], v[138:139]
	v_pk_fma_f32 v[142:143], v[120:121], v[56:57], v[142:143]
	v_pk_fma_f32 v[136:137], v[98:99], v[50:51], v[136:137]
	v_pk_fma_f32 v[140:141], v[114:115], v[50:51], v[140:141]
	v_pk_fma_f32 v[138:139], v[106:107], v[58:59], v[138:139]
	v_pk_fma_f32 v[142:143], v[122:123], v[58:59], v[142:143]
	v_pk_add_f32 v[136:137], v[136:137], v[138:139]
	v_pk_add_f32 v[140:141], v[140:141], v[142:143]
	v_add_f32_e32 v76, v136, v137
	v_add_f32_e32 v77, v140, v141
	s_cmp_le_u32 s91, 10
	s_cbranch_scc1 .Lu3_dotsdone
	v_cvt_pk_f32_fp8_e32 v[92:93], v196
	v_cvt_pk_f32_fp8_e32 v[108:109], v200
	v_cvt_pk_f32_fp8_sdwa v[94:95], v196 src0_sel:WORD_1
	v_cvt_pk_f32_fp8_sdwa v[110:111], v200 src0_sel:WORD_1
	v_cvt_pk_f32_fp8_e32 v[96:97], v197
	v_cvt_pk_f32_fp8_e32 v[112:113], v201
	v_cvt_pk_f32_fp8_sdwa v[98:99], v197 src0_sel:WORD_1
	v_cvt_pk_f32_fp8_sdwa v[114:115], v201 src0_sel:WORD_1
	v_cvt_pk_f32_fp8_e32 v[100:101], v198
	v_cvt_pk_f32_fp8_e32 v[116:117], v202
	v_cvt_pk_f32_fp8_sdwa v[102:103], v198 src0_sel:WORD_1
	v_cvt_pk_f32_fp8_sdwa v[118:119], v202 src0_sel:WORD_1
	v_cvt_pk_f32_fp8_e32 v[104:105], v199
	v_cvt_pk_f32_fp8_e32 v[120:121], v203
	v_cvt_pk_f32_fp8_sdwa v[106:107], v199 src0_sel:WORD_1
	v_cvt_pk_f32_fp8_sdwa v[122:123], v203 src0_sel:WORD_1
	v_pk_mul_f32 v[136:137], v[92:93], v[44:45]
	v_pk_mul_f32 v[140:141], v[108:109], v[44:45]
	v_pk_mul_f32 v[138:139], v[100:101], v[52:53]
	v_pk_mul_f32 v[142:143], v[116:117], v[52:53]
	v_pk_fma_f32 v[136:137], v[94:95], v[46:47], v[136:137]
	v_pk_fma_f32 v[140:141], v[110:111], v[46:47], v[140:141]
	v_pk_fma_f32 v[138:139], v[102:103], v[54:55], v[138:139]
	v_pk_fma_f32 v[142:143], v[118:119], v[54:55], v[142:143]
	v_pk_fma_f32 v[136:137], v[96:97], v[48:49], v[136:137]
	v_pk_fma_f32 v[140:141], v[112:113], v[48:49], v[140:141]
	v_pk_fma_f32 v[138:139], v[104:105], v[56:57], v[138:139]
	v_pk_fma_f32 v[142:143], v[120:121], v[56:57], v[142:143]
	v_pk_fma_f32 v[136:137], v[98:99], v[50:51], v[136:137]
	v_pk_fma_f32 v[140:141], v[114:115], v[50:51], v[140:141]
	v_pk_fma_f32 v[138:139], v[106:107], v[58:59], v[138:139]
	v_pk_fma_f32 v[142:143], v[122:123], v[58:59], v[142:143]
	v_pk_add_f32 v[136:137], v[136:137], v[138:139]
	v_pk_add_f32 v[140:141], v[140:141], v[142:143]
	v_add_f32_e32 v78, v136, v137
	v_add_f32_e32 v79, v140, v141
	s_cmp_le_u32 s91, 12
	s_cbranch_scc1 .Lu3_dotsdone
; #define AS1 __attribute__((address_space(1)))
; DI float dot16_fp8(u32x4 u, const float* x, float c) {
;   const unsigned d[4] = {u[0], u[1], u[2], u[3]};
; #pragma unroll
;   for (int i = 0; i < 4; ++i) {
;     f32x2 a = __builtin_amdgcn_cvt_pk_f32_fp8((int)d[i], false);
;     f32x2 b = __builtin_amdgcn_cvt_pk_f32_fp8((int)d[i], true);
;     c += a[0] * x[4 * i] + a[1] * x[4 * i + 1] + b[0] * x[4 * i + 2] + b[1] * x[4 * i + 3];
;   }
;   return c;
; }
; DI void peer_u_wave(const Params& p, int row, float* wl  ) {
;     ...
; #pragma unroll
;     for (int e = 0; e < 64; ++e) {
;       const int id = __builtin_amdgcn_readlane(eidv, e);
;       const u32x4 u = *(const u32x4 AS1*)(EU8 + (size_t)id * 1024 + lane * 16);
;       part[e] = dot16_fp8(u, xf, 0.f);
;     }
	v_cvt_pk_f32_fp8_e32 v[92:93], v204
	v_cvt_pk_f32_fp8_e32 v[108:109], v208
	v_cvt_pk_f32_fp8_sdwa v[94:95], v204 src0_sel:WORD_1
	v_cvt_pk_f32_fp8_sdwa v[110:111], v208 src0_sel:WORD_1
	v_cvt_pk_f32_fp8_e32 v[96:97], v205
	v_cvt_pk_f32_fp8_e32 v[112:113], v209
	v_cvt_pk_f32_fp8_sdwa v[98:99], v205 src0_sel:WORD_1
	v_cvt_pk_f32_fp8_sdwa v[114:115], v209 src0_sel:WORD_1
	v_cvt_pk_f32_fp8_e32 v[100:101], v206
	v_cvt_pk_f32_fp8_e32 v[116:117], v210
	v_cvt_pk_f32_fp8_sdwa v[102:103], v206 src0_sel:WORD_1
	v_cvt_pk_f32_fp8_sdwa v[118:119], v210 src0_sel:WORD_1
	v_cvt_pk_f32_fp8_e32 v[104:105], v207
	v_cvt_pk_f32_fp8_e32 v[120:121], v211
	v_cvt_pk_f32_fp8_sdwa v[106:107], v207 src0_sel:WORD_1
	v_cvt_pk_f32_fp8_sdwa v[122:123], v211 src0_sel:WORD_1
	v_pk_mul_f32 v[136:137], v[92:93], v[44:45]
	v_pk_mul_f32 v[140:141], v[108:109], v[44:45]
	v_pk_mul_f32 v[138:139], v[100:101], v[52:53]
	v_pk_mul_f32 v[142:143], v[116:117], v[52:53]
	v_pk_fma_f32 v[136:137], v[94:95], v[46:47], v[136:137]
	v_pk_fma_f32 v[140:141], v[110:111], v[46:47], v[140:141]
	v_pk_fma_f32 v[138:139], v[102:103], v[54:55], v[138:139]
	v_pk_fma_f32 v[142:143], v[118:119], v[54:55], v[142:143]
	v_pk_fma_f32 v[136:137], v[96:97], v[48:49], v[136:137]
	v_pk_fma_f32 v[140:141], v[112:113], v[48:49], v[140:141]
	v_pk_fma_f32 v[138:139], v[104:105], v[56:57], v[138:139]
	v_pk_fma_f32 v[142:143], v[120:121], v[56:57], v[142:143]
	v_pk_fma_f32 v[136:137], v[98:99], v[50:51], v[136:137]
	v_pk_fma_f32 v[140:141], v[114:115], v[50:51], v[140:141]
	v_pk_fma_f32 v[138:139], v[106:107], v[58:59], v[138:139]
	v_pk_fma_f32 v[142:143], v[122:123], v[58:59], v[142:143]
	v_pk_add_f32 v[136:137], v[136:137], v[138:139]
	v_pk_add_f32 v[140:141], v[140:141], v[142:143]
	v_add_f32_e32 v80, v136, v137
	v_add_f32_e32 v81, v140, v141
	s_cmp_le_u32 s91, 14
	s_cbranch_scc1 .Lu3_dotsdone
	v_cvt_pk_f32_fp8_e32 v[92:93], v212
	v_cvt_pk_f32_fp8_e32 v[108:109], v216
	v_cvt_pk_f32_fp8_sdwa v[94:95], v212 src0_sel:WORD_1
	v_cvt_pk_f32_fp8_sdwa v[110:111], v216 src0_sel:WORD_1
	v_cvt_pk_f32_fp8_e32 v[96:97], v213
	v_cvt_pk_f32_fp8_e32 v[112:113], v217
	v_cvt_pk_f32_fp8_sdwa v[98:99], v213 src0_sel:WORD_1
	v_cvt_pk_f32_fp8_sdwa v[114:115], v217 src0_sel:WORD_1
	v_cvt_pk_f32_fp8_e32 v[100:101], v214
	v_cvt_pk_f32_fp8_e32 v[116:117], v218
	v_cvt_pk_f32_fp8_sdwa v[102:103], v214 src0_sel:WORD_1
	v_cvt_pk_f32_fp8_sdwa v[118:119], v218 src0_sel:WORD_1
	v_cvt_pk_f32_fp8_e32 v[104:105], v215
	v_cvt_pk_f32_fp8_e32 v[120:121], v219
	v_cvt_pk_f32_fp8_sdwa v[106:107], v215 src0_sel:WORD_1
	v_cvt_pk_f32_fp8_sdwa v[122:123], v219 src0_sel:WORD_1
	v_pk_mul_f32 v[136:137], v[92:93], v[44:45]
	v_pk_mul_f32 v[140:141], v[108:109], v[44:45]
	v_pk_mul_f32 v[138:139], v[100:101], v[52:53]
	v_pk_mul_f32 v[142:143], v[116:117], v[52:53]
	v_pk_fma_f32 v[136:137], v[94:95], v[46:47], v[136:137]
	v_pk_fma_f32 v[140:141], v[110:111], v[46:47], v[140:141]
	v_pk_fma_f32 v[138:139], v[102:103], v[54:55], v[138:139]
	v_pk_fma_f32 v[142:143], v[118:119], v[54:55], v[142:143]
	v_pk_fma_f32 v[136:137], v[96:97], v[48:49], v[136:137]
	v_pk_fma_f32 v[140:141], v[112:113], v[48:49], v[140:141]
	v_pk_fma_f32 v[138:139], v[104:105], v[56:57], v[138:139]
	v_pk_fma_f32 v[142:143], v[120:121], v[56:57], v[142:143]
	v_pk_fma_f32 v[136:137], v[98:99], v[50:51], v[136:137]
	v_pk_fma_f32 v[140:141], v[114:115], v[50:51], v[140:141]
	v_pk_fma_f32 v[138:139], v[106:107], v[58:59], v[138:139]
	v_pk_fma_f32 v[142:143], v[122:123], v[58:59], v[142:143]
	v_pk_add_f32 v[136:137], v[136:137], v[138:139]
	v_pk_add_f32 v[140:141], v[140:141], v[142:143]
	v_add_f32_e32 v82, v136, v137
	v_add_f32_e32 v83, v140, v141
	s_cmp_le_u32 s91, 16
	s_cbranch_scc1 .Lu3_dotsdone
	v_cvt_pk_f32_fp8_e32 v[92:93], v220
	v_cvt_pk_f32_fp8_e32 v[108:109], v224
	v_cvt_pk_f32_fp8_sdwa v[94:95], v220 src0_sel:WORD_1
	v_cvt_pk_f32_fp8_sdwa v[110:111], v224 src0_sel:WORD_1
	v_cvt_pk_f32_fp8_e32 v[96:97], v221
	v_cvt_pk_f32_fp8_e32 v[112:113], v225
	v_cvt_pk_f32_fp8_sdwa v[98:99], v221 src0_sel:WORD_1
	v_cvt_pk_f32_fp8_sdwa v[114:115], v225 src0_sel:WORD_1
	v_cvt_pk_f32_fp8_e32 v[100:101], v222
	v_cvt_pk_f32_fp8_e32 v[116:117], v226
	v_cvt_pk_f32_fp8_sdwa v[102:103], v222 src0_sel:WORD_1
	v_cvt_pk_f32_fp8_sdwa v[118:119], v226 src0_sel:WORD_1
	v_cvt_pk_f32_fp8_e32 v[104:105], v223
	v_cvt_pk_f32_fp8_e32 v[120:121], v227
	v_cvt_pk_f32_fp8_sdwa v[106:107], v223 src0_sel:WORD_1
	v_cvt_pk_f32_fp8_sdwa v[122:123], v227 src0_sel:WORD_1
	v_pk_mul_f32 v[136:137], v[92:93], v[44:45]
	v_pk_mul_f32 v[140:141], v[108:109], v[44:45]
	v_pk_mul_f32 v[138:139], v[100:101], v[52:53]
	v_pk_mul_f32 v[142:143], v[116:117], v[52:53]
	v_pk_fma_f32 v[136:137], v[94:95], v[46:47], v[136:137]
	v_pk_fma_f32 v[140:141], v[110:111], v[46:47], v[140:141]
	v_pk_fma_f32 v[138:139], v[102:103], v[54:55], v[138:139]
	v_pk_fma_f32 v[142:143], v[118:119], v[54:55], v[142:143]
	v_pk_fma_f32 v[136:137], v[96:97], v[48:49], v[136:137]
	v_pk_fma_f32 v[140:141], v[112:113], v[48:49], v[140:141]
	v_pk_fma_f32 v[138:139], v[104:105], v[56:57], v[138:139]
	v_pk_fma_f32 v[142:143], v[120:121], v[56:57], v[142:143]
	v_pk_fma_f32 v[136:137], v[98:99], v[50:51], v[136:137]
	v_pk_fma_f32 v[140:141], v[114:115], v[50:51], v[140:141]
	v_pk_fma_f32 v[138:139], v[106:107], v[58:59], v[138:139]
	v_pk_fma_f32 v[142:143], v[122:123], v[58:59], v[142:143]
	v_pk_add_f32 v[136:137], v[136:137], v[138:139]
	v_pk_add_f32 v[140:141], v[140:141], v[142:143]
	v_add_f32_e32 v84, v136, v137
	v_add_f32_e32 v85, v140, v141
	s_cmp_le_u32 s91, 18
	s_cbranch_scc1 .Lu3_dotsdone
; #define AS1 __attribute__((address_space(1)))
; DI float dot16_fp8(u32x4 u, const float* x, float c) {
;   const unsigned d[4] = {u[0], u[1], u[2], u[3]};
; #pragma unroll
;   for (int i = 0; i < 4; ++i) {
;     f32x2 a = __builtin_amdgcn_cvt_pk_f32_fp8((int)d[i], false);
;     f32x2 b = __builtin_amdgcn_cvt_pk_f32_fp8((int)d[i], true);
;     c += a[0] * x[4 * i] + a[1] * x[4 * i + 1] + b[0] * x[4 * i + 2] + b[1] * x[4 * i + 3];
;   }
;   return c;
; }
; DI void peer_u_wave(const Params& p, int row, float* wl  ) {
;     ...
; #pragma unroll
;     for (int e = 0; e < 64; ++e) {
;       const int id = __builtin_amdgcn_readlane(eidv, e);
;       const u32x4 u = *(const u32x4 AS1*)(EU8 + (size_t)id * 1024 + lane * 16);
;       part[e] = dot16_fp8(u, xf, 0.f);
;     }
	v_cvt_pk_f32_fp8_e32 v[92:93], v228
	v_cvt_pk_f32_fp8_e32 v[108:109], v232
	v_cvt_pk_f32_fp8_sdwa v[94:95], v228 src0_sel:WORD_1
	v_cvt_pk_f32_fp8_sdwa v[110:111], v232 src0_sel:WORD_1
	v_cvt_pk_f32_fp8_e32 v[96:97], v229
	v_cvt_pk_f32_fp8_e32 v[112:113], v233
	v_cvt_pk_f32_fp8_sdwa v[98:99], v229 src0_sel:WORD_1
	v_cvt_pk_f32_fp8_sdwa v[114:115], v233 src0_sel:WORD_1
	v_cvt_pk_f32_fp8_e32 v[100:101], v230
	v_cvt_pk_f32_fp8_e32 v[116:117], v234
	v_cvt_pk_f32_fp8_sdwa v[102:103], v230 src0_sel:WORD_1
	v_cvt_pk_f32_fp8_sdwa v[118:119], v234 src0_sel:WORD_1
	v_cvt_pk_f32_fp8_e32 v[104:105], v231
	v_cvt_pk_f32_fp8_e32 v[120:121], v235
	v_cvt_pk_f32_fp8_sdwa v[106:107], v231 src0_sel:WORD_1
	v_cvt_pk_f32_fp8_sdwa v[122:123], v235 src0_sel:WORD_1
	v_pk_mul_f32 v[136:137], v[92:93], v[44:45]
	v_pk_mul_f32 v[140:141], v[108:109], v[44:45]
	v_pk_mul_f32 v[138:139], v[100:101], v[52:53]
	v_pk_mul_f32 v[142:143], v[116:117], v[52:53]
	v_pk_fma_f32 v[136:137], v[94:95], v[46:47], v[136:137]
	v_pk_fma_f32 v[140:141], v[110:111], v[46:47], v[140:141]
	v_pk_fma_f32 v[138:139], v[102:103], v[54:55], v[138:139]
	v_pk_fma_f32 v[142:143], v[118:119], v[54:55], v[142:143]
	v_pk_fma_f32 v[136:137], v[96:97], v[48:49], v[136:137]
	v_pk_fma_f32 v[140:141], v[112:113], v[48:49], v[140:141]
	v_pk_fma_f32 v[138:139], v[104:105], v[56:57], v[138:139]
	v_pk_fma_f32 v[142:143], v[120:121], v[56:57], v[142:143]
	v_pk_fma_f32 v[136:137], v[98:99], v[50:51], v[136:137]
	v_pk_fma_f32 v[140:141], v[114:115], v[50:51], v[140:141]
	v_pk_fma_f32 v[138:139], v[106:107], v[58:59], v[138:139]
	v_pk_fma_f32 v[142:143], v[122:123], v[58:59], v[142:143]
	v_pk_add_f32 v[136:137], v[136:137], v[138:139]
	v_pk_add_f32 v[140:141], v[140:141], v[142:143]
	v_add_f32_e32 v86, v136, v137
	v_add_f32_e32 v87, v140, v141
	s_cmp_le_u32 s91, 20
	s_cbranch_scc1 .Lu3_dotsdone
	v_cvt_pk_f32_fp8_e32 v[92:93], v236
	v_cvt_pk_f32_fp8_e32 v[108:109], v240
	v_cvt_pk_f32_fp8_sdwa v[94:95], v236 src0_sel:WORD_1
	v_cvt_pk_f32_fp8_sdwa v[110:111], v240 src0_sel:WORD_1
	v_cvt_pk_f32_fp8_e32 v[96:97], v237
	v_cvt_pk_f32_fp8_e32 v[112:113], v241
	v_cvt_pk_f32_fp8_sdwa v[98:99], v237 src0_sel:WORD_1
	v_cvt_pk_f32_fp8_sdwa v[114:115], v241 src0_sel:WORD_1
	v_cvt_pk_f32_fp8_e32 v[100:101], v238
	v_cvt_pk_f32_fp8_e32 v[116:117], v242
	v_cvt_pk_f32_fp8_sdwa v[102:103], v238 src0_sel:WORD_1
	v_cvt_pk_f32_fp8_sdwa v[118:119], v242 src0_sel:WORD_1
	v_cvt_pk_f32_fp8_e32 v[104:105], v239
	v_cvt_pk_f32_fp8_e32 v[120:121], v243
	v_cvt_pk_f32_fp8_sdwa v[106:107], v239 src0_sel:WORD_1
	v_cvt_pk_f32_fp8_sdwa v[122:123], v243 src0_sel:WORD_1
	v_pk_mul_f32 v[136:137], v[92:93], v[44:45]
	v_pk_mul_f32 v[140:141], v[108:109], v[44:45]
	v_pk_mul_f32 v[138:139], v[100:101], v[52:53]
	v_pk_mul_f32 v[142:143], v[116:117], v[52:53]
	v_pk_fma_f32 v[136:137], v[94:95], v[46:47], v[136:137]
	v_pk_fma_f32 v[140:141], v[110:111], v[46:47], v[140:141]
	v_pk_fma_f32 v[138:139], v[102:103], v[54:55], v[138:139]
	v_pk_fma_f32 v[142:143], v[118:119], v[54:55], v[142:143]
	v_pk_fma_f32 v[136:137], v[96:97], v[48:49], v[136:137]
	v_pk_fma_f32 v[140:141], v[112:113], v[48:49], v[140:141]
	v_pk_fma_f32 v[138:139], v[104:105], v[56:57], v[138:139]
	v_pk_fma_f32 v[142:143], v[120:121], v[56:57], v[142:143]
	v_pk_fma_f32 v[136:137], v[98:99], v[50:51], v[136:137]
	v_pk_fma_f32 v[140:141], v[114:115], v[50:51], v[140:141]
	v_pk_fma_f32 v[138:139], v[106:107], v[58:59], v[138:139]
	v_pk_fma_f32 v[142:143], v[122:123], v[58:59], v[142:143]
	v_pk_add_f32 v[136:137], v[136:137], v[138:139]
	v_pk_add_f32 v[140:141], v[140:141], v[142:143]
	v_add_f32_e32 v88, v136, v137
	v_add_f32_e32 v89, v140, v141
	s_cmp_le_u32 s91, 22
	s_cbranch_scc1 .Lu3_dotsdone
	v_cvt_pk_f32_fp8_e32 v[92:93], v244
	v_cvt_pk_f32_fp8_e32 v[108:109], v248
	v_cvt_pk_f32_fp8_sdwa v[94:95], v244 src0_sel:WORD_1
	v_cvt_pk_f32_fp8_sdwa v[110:111], v248 src0_sel:WORD_1
	v_cvt_pk_f32_fp8_e32 v[96:97], v245
	v_cvt_pk_f32_fp8_e32 v[112:113], v249
	v_cvt_pk_f32_fp8_sdwa v[98:99], v245 src0_sel:WORD_1
	v_cvt_pk_f32_fp8_sdwa v[114:115], v249 src0_sel:WORD_1
	v_cvt_pk_f32_fp8_e32 v[100:101], v246
	v_cvt_pk_f32_fp8_e32 v[116:117], v250
	v_cvt_pk_f32_fp8_sdwa v[102:103], v246 src0_sel:WORD_1
	v_cvt_pk_f32_fp8_sdwa v[118:119], v250 src0_sel:WORD_1
	v_cvt_pk_f32_fp8_e32 v[104:105], v247
	v_cvt_pk_f32_fp8_e32 v[120:121], v251
	v_cvt_pk_f32_fp8_sdwa v[106:107], v247 src0_sel:WORD_1
	v_cvt_pk_f32_fp8_sdwa v[122:123], v251 src0_sel:WORD_1
	v_pk_mul_f32 v[136:137], v[92:93], v[44:45]
	v_pk_mul_f32 v[140:141], v[108:109], v[44:45]
	v_pk_mul_f32 v[138:139], v[100:101], v[52:53]
	v_pk_mul_f32 v[142:143], v[116:117], v[52:53]
	v_pk_fma_f32 v[136:137], v[94:95], v[46:47], v[136:137]
	v_pk_fma_f32 v[140:141], v[110:111], v[46:47], v[140:141]
	v_pk_fma_f32 v[138:139], v[102:103], v[54:55], v[138:139]
	v_pk_fma_f32 v[142:143], v[118:119], v[54:55], v[142:143]
	v_pk_fma_f32 v[136:137], v[96:97], v[48:49], v[136:137]
	v_pk_fma_f32 v[140:141], v[112:113], v[48:49], v[140:141]
	v_pk_fma_f32 v[138:139], v[104:105], v[56:57], v[138:139]
	v_pk_fma_f32 v[142:143], v[120:121], v[56:57], v[142:143]
	v_pk_fma_f32 v[136:137], v[98:99], v[50:51], v[136:137]
	v_pk_fma_f32 v[140:141], v[114:115], v[50:51], v[140:141]
	v_pk_fma_f32 v[138:139], v[106:107], v[58:59], v[138:139]
	v_pk_fma_f32 v[142:143], v[122:123], v[58:59], v[142:143]
	v_pk_add_f32 v[136:137], v[136:137], v[138:139]
	v_pk_add_f32 v[140:141], v[140:141], v[142:143]
	v_add_f32_e32 v90, v136, v137
	v_add_f32_e32 v91, v140, v141
; #define AS1 __attribute__((address_space(1)))
; DI float geluf(float x) { return 0.5f * x * (1.f + tanhf(0.7978845608028654f * (x + 0.044715f * x * x * x))); }
; DI void peer_u_wave(const Params& p, int row, float* wl  ) {
;     ...
;   for (int bt = 0; bt < 2; ++bt) {
;     const int eidv = ((const int AS1*)p.eid)[(size_t)row * 128 + bt * 64 + lane];
;     const float gv = ((const float AS1*)p.gate)[(size_t)row * 128 + bt * 64 + lane];
;     const float rsu = rsp[eidv], rsv = rsp[16384 + eidv];
;     float part[64];
; #pragma unroll
;     for (int e = 0; e < 64; ++e) {
;       const int id = __builtin_amdgcn_readlane(eidv, e);
;       const u32x4 u = *(const u32x4 AS1*)(EU8 + (size_t)id * 1024 + lane * 16);
;       part[e] = dot16_fp8(u, xf, 0.f);
;     }
; #pragma unroll
;     for (int off = 32; off > 0; off >>= 1) {
;       const bool up = (lane & off) != 0;
; #pragma unroll
;       for (int i = 0; i < off; ++i) {
;         const float a = part[i], bq = part[i + off];
;         const float send = up ? a : bq, keep = up ? bq : a;
;         part[i] = keep + __shfl_xor(send, off);
;       }
;     }
;     wl[bt * 64 + lane] = gv * geluf(part[0] * r2 * rsu) * rsv;
;   }
; __global__ void __launch_bounds__(256, 2) mega(Params pk) {
;     ...
;     for (int k = 0; gw + k * nw < MT && k < 17; ++k) peer_u_wave(p, gw + k * nw, wlw + k * 128);
;     __builtin_amdgcn_s_waitcnt(0xc07f);
;     __builtin_amdgcn_wave_barrier();
;     for (int g = 0; (g * 4) * nw + gw < MT && g < 5; ++g) peer_v_group(p, gw, nw, g, wlw);
.Lu3_dotsdone:
	s_cmp_gt_i32 s4, 0
	s_cbranch_scc0 .Lu3_lateend
	s_mov_b32 s92, 1
	s_branch .Lu3_tail
.Lu3_ovf_cont:
	s_mov_b32 s92, 0
	s_add_u32 s59, s59, 3
	s_min_u32 s58, s4, 24
	s_sub_i32 s4, s4, 24
	s_lshl_b32 s63, s59, 5
	v_add_u32_e32 v10, s63, v67
	ds_read_b32 v254, v10
	s_mov_b32 s96, 1
	s_waitcnt lgkmcnt(0)
	s_branch .Lu3_gather
.Lu3_ovf_g2:
	s_mov_b32 s96, 0
	s_mov_b32 s91, s58
	s_waitcnt vmcnt(0)
	s_branch .Lu3_dots
.Lu3_lateend:
	s_mov_b32 s89, 1
	s_mov_b32 s88, s37
	s_cmp_eq_u32 s37, 0
	s_cbranch_scc1 .Lu3_top
	s_waitcnt vmcnt(0)
	v_mov_b32_e32 v12, v28
	v_mov_b32_e32 v13, v29
	v_mov_b32_e32 v14, v30
	v_mov_b32_e32 v15, v31
	v_mov_b32_e32 v16, v32
	v_mov_b32_e32 v17, v33
	v_mov_b32_e32 v18, v34
	v_mov_b32_e32 v19, v35
	v_mov_b32_e32 v20, v36
	v_mov_b32_e32 v21, v37
	v_mov_b32_e32 v22, v38
	v_mov_b32_e32 v23, v39
	v_mov_b32_e32 v24, v41
	s_mov_b32 s34, s36
	s_branch .Lu3_top
.Lu3_done:
	s_mov_b64 exec, -1
	s_waitcnt vmcnt(0)
	v_mov_b32_e32 v163, v252
	v_mov_b32_e32 v174, v253
.LBB0_1357:
	s_or_b64 exec, exec, s[14:15]
	s_waitcnt lgkmcnt(0)
	s_waitcnt vmcnt(0)
	s_barrier
	v_readlane_b32 s92, v255, 0
	v_readlane_b32 s93, v255, 1
	s_mov_b64 s[90:91], exec
	s_and_b64 exec, exec, s[92:93]
	s_cbranch_execz .Lgb_skip
	buffer_wbl2 sc1
	s_waitcnt vmcnt(0)
	v_mov_b32_e32 v222, 0x101e8
	ds_read_b64 v[224:225], v222
	v_mov_b32_e32 v222, 1
	s_waitcnt lgkmcnt(0)
	flat_atomic_add v[224:225], v222 offset:256
	s_waitcnt vmcnt(0) lgkmcnt(0)
.Lgb_spin:
	s_sleep 2
	flat_load_dword v223, v[224:225] offset:256 sc1
	s_waitcnt vmcnt(0) lgkmcnt(0)
	v_readfirstlane_b32 s92, v223
	s_nop 3
	s_cmp_lt_u32 s92, s84
	s_cbranch_scc1 .Lgb_spin
	buffer_inv sc1
.Lgb_skip:
	s_mov_b64 exec, s[90:91]
	s_barrier
	s_and_b64 exec, exec, s[8:9]
	s_cbranch_execz .LBB0_1578
	v_mov_b32_e32 v0, 0x10120
	ds_read_b64 v[0:1], v0
	v_mov_b32_e32 v37, 0
	v_lshlrev_b32_e32 v38, 4, v128
	v_mov_b32_e32 v39, v37
	v_lshlrev_b32_e32 v4, 2, v128
	s_waitcnt lgkmcnt(0)
	v_lshl_add_u64 v[0:1], v[0:1], 0, v[38:39]
	s_mov_b64 s[0:1], 0x1000000
	v_add_u32_e32 v129, v40, v4
	v_lshl_add_u64 v[40:41], v[0:1], 0, s[0:1]
	v_and_b32_e32 v0, 64, v128
	v_add_u32_e32 v5, 64, v0
	v_xor_b32_e32 v0, 32, v128
	v_cmp_lt_i32_e32 vcc, v0, v5
	v_mov_b32_e32 v2, 0x101b0
	v_mov_b32_e32 v3, 0x10170
	v_cndmask_b32_e32 v0, v128, v0, vcc
	v_lshlrev_b32_e32 v39, 2, v0
	v_xor_b32_e32 v0, 16, v128
	v_cmp_lt_i32_e32 vcc, v0, v5
	ds_read_b64 v[6:7], v2
	ds_read_b64 v[2:3], v3
	v_cndmask_b32_e32 v0, v128, v0, vcc
	v_lshlrev_b32_e32 v130, 2, v0
	v_xor_b32_e32 v0, 8, v128
	v_cmp_lt_i32_e32 vcc, v0, v5
	v_lshlrev_b32_e32 v36, 5, v128
	s_waitcnt lgkmcnt(0)
	v_lshl_add_u64 v[42:43], v[2:3], 0, v[36:37]
	v_cndmask_b32_e32 v0, v128, v0, vcc
	v_lshlrev_b32_e32 v131, 2, v0
	v_xor_b32_e32 v0, 4, v128
	v_cmp_lt_i32_e32 vcc, v0, v5
	v_xor_b32_e32 v8, 1, v128
	s_mov_b64 s[0:1], 0x8000000
	v_cndmask_b32_e32 v0, v128, v0, vcc
	v_lshlrev_b32_e32 v132, 2, v0
	v_xor_b32_e32 v0, 2, v128
	v_cmp_lt_i32_e32 vcc, v0, v5
	v_lshlrev_b32_e32 v36, 6, v128
	s_mov_b32 s10, 0
	v_cndmask_b32_e32 v0, v128, v0, vcc
	v_lshlrev_b32_e32 v133, 2, v0
	v_mov_b32_e32 v0, 0x100d0
	ds_read_b128 v[0:3], v0
	v_cmp_lt_i32_e32 vcc, v8, v5
	s_mov_b64 s[8:9], 0
	s_mov_b32 s13, 0x8080
	v_cndmask_b32_e32 v5, v128, v8, vcc
	v_lshlrev_b32_e32 v134, 2, v5
	v_mov_b32_e32 v5, v37
	s_waitcnt lgkmcnt(0)
	v_lshl_add_u64 v[44:45], v[2:3], 0, s[0:1]
	v_lshl_add_u64 v[0:1], v[0:1], 0, v[36:37]
	v_lshl_add_u64 v[46:47], v[6:7], 0, v[4:5]
	s_mov_b32 s33, 0x8000
	v_mov_b32_e32 v128, 0x358637bd
	s_mov_b32 s34, 0x800000
	s_mov_b32 s35, 0x807f
	v_mov_b32_e32 v86, v163
	s_mov_b32 s36, 0
	s_branch .LBB0_1360

; #define AS1 __attribute__((address_space(1)))
; DI void peer_v_group(const Params& p, int gw, int nw, int g, const float* wlw  ) {
;     ...
; #pragma unroll
;   for (int ts = 0; ts < 4; ++ts) {
;     const int k = g * 4 + ts;
;     const int row = gw + k * nw;
;     valid[ts] = row < MT;
; #pragma unroll
;     for (int i = 0; i < 16; ++i) out[ts][i] = 0.f;
;     e0[ts] = 0x7fffffff; e1[ts] = 0x7fffffff; w0[ts] = 0.f; w1[ts] = 0.f;
;     if (valid[ts]) {
;       e0[ts] = ((const int AS1*)p.eid)[(size_t)row * 128 + lane];
;       e1[ts] = ((const int AS1*)p.eid)[(size_t)row * 128 + 64 + lane];
;       w0[ts] = wlw[k * 128 + lane];
;       w1[ts] = wlw[k * 128 + 64 + lane];
;     }
;   }
.LBB0_1360:
	v_ashrrev_i32_e32 v87, 31, v86
	v_lshlrev_b64 v[4:5], 9, v[86:87]
	v_lshl_add_u64 v[4:5], v[46:47], 0, v[4:5]
	global_load_dword v135, v[4:5], off
	global_load_dword v136, v[4:5], off offset:256
	v_lshl_add_u64 v[222:223], v[4:5], 0, s[94:95]
	global_load_dword v104, v[222:223], off
	global_load_dword v105, v[222:223], off offset:256
	s_or_b32 s2, s10, 1
	s_mul_i32 s0, s2, s78
	v_add_u32_e32 v68, s0, v163
	v_cmp_gt_i32_e64 s[4:5], s13, v68
	v_bfrev_b32_e32 v51, -2
	v_bfrev_b32_e32 v69, -2
	v_bfrev_b32_e32 v137, -2
	v_mov_b32_e32 v106, 0
	v_mov_b32_e32 v107, 0
	s_and_saveexec_b64 s[0:1], s[4:5]
	s_cbranch_execz .LBB0_1362
	v_ashrrev_i32_e32 v69, 31, v68
	v_lshlrev_b64 v[4:5], 9, v[68:69]
	v_lshl_add_u64 v[4:5], v[46:47], 0, v[4:5]
	global_load_dword v69, v[4:5], off
	global_load_dword v137, v[4:5], off offset:256
	v_lshl_add_u64 v[222:223], v[4:5], 0, s[94:95]
	global_load_dword v106, v[222:223], off
	global_load_dword v107, v[222:223], off offset:256
.LBB0_1362:
	s_or_b64 exec, exec, s[0:1]
	v_add_u32_e32 v50, s78, v68
	v_cmp_gt_i32_e64 s[2:3], s13, v50
	v_mov_b32_e32 v108, 0
	v_bfrev_b32_e32 v138, -2
	v_mov_b32_e32 v110, 0
	v_mov_b32_e32 v111, 0
	s_and_saveexec_b64 s[0:1], s[2:3]
	s_cbranch_execz .LBB0_1364
	v_ashrrev_i32_e32 v51, 31, v50
	v_lshlrev_b64 v[4:5], 9, v[50:51]
	v_lshl_add_u64 v[4:5], v[46:47], 0, v[4:5]
	global_load_dword v51, v[4:5], off
	global_load_dword v138, v[4:5], off offset:256
	v_lshl_add_u64 v[222:223], v[4:5], 0, s[94:95]
	global_load_dword v110, v[222:223], off
	global_load_dword v111, v[222:223], off offset:256
.LBB0_1364:
	s_or_b64 exec, exec, s[0:1]
	v_add_u32_e32 v48, s78, v50
	v_cmp_gt_i32_e64 s[0:1], s13, v48
	v_bfrev_b32_e32 v49, -2
	v_bfrev_b32_e32 v139, -2
	v_mov_b32_e32 v109, 0
	s_and_saveexec_b64 s[6:7], s[0:1]
	s_cbranch_execz .LBB0_1366
	v_ashrrev_i32_e32 v49, 31, v48
	v_lshlrev_b64 v[4:5], 9, v[48:49]
	v_lshl_add_u64 v[4:5], v[46:47], 0, v[4:5]
	global_load_dword v49, v[4:5], off
	global_load_dword v139, v[4:5], off offset:256
	v_lshl_add_u64 v[222:223], v[4:5], 0, s[94:95]
	global_load_dword v108, v[222:223], off
	global_load_dword v109, v[222:223], off offset:256
